# P0: f64 discretisation block and the second Lambda^d element moved from workgroups 0..7 to the lightly loaded 128..143 (grid 256 only)
# baseline (speedup 1.0000x reference)
; #define GIN(i) GPTR(const float, args.in[i])
; __device__ __forceinline__ void dsincos(double x, double& s, double& c) {
;     const double k = __builtin_rint(x * 0.63661977236758134308);
;     double r = __builtin_fma(-k, 1.57079632679489655800e+00, x);
;     r = __builtin_fma(-k, 6.12323399573676603587e-17, r);
;     const int q = (int)k & 3;
;     const double z = r * r;
;     double sp = -1.0 / 1307674368000.0; sp = sp * z + 1.0 / 6227020800.0; sp = sp * z - 1.0 / 39916800.0; sp = sp * z + 1.0 / 362880.0; sp = sp * z - 1.0 / 5040.0; sp = sp * z + 1.0 / 120.0; sp = sp * z - 1.0 / 6.0; sp = sp * z + 1.0; sp = sp * r;
;     double cp = -1.0 / 87178291200.0; cp = cp * z + 1.0 / 479001600.0; cp = cp * z - 1.0 / 3628800.0; cp = cp * z + 1.0 / 40320.0; cp = cp * z - 1.0 / 720.0; cp = cp * z + 1.0 / 24.0; cp = cp * z - 0.5; cp = cp * z + 1.0;
;     s = (q == 0) ? sp : (q == 1) ? cp : (q == 2) ? -sp : -cp;
;     c = (q == 0) ? cp : (q == 1) ? -sp : (q == 2) ? -cp : sp;
; }
; __device__ __forceinline__ double dexp(double x) {
;     const double k = __builtin_rint(x * 1.44269504088896338700e+00);
;     double r = __builtin_fma(-k, 6.93147180369123816490e-01, x);
;     r = __builtin_fma(-k, 1.90821492927058770002e-10, r);
;     double p = 1.0 / 6227020800.0;
;     p = p * r + 1.0 / 479001600.0; p = p * r + 1.0 / 39916800.0; p = p * r + 1.0 / 3628800.0; p = p * r + 1.0 / 362880.0; p = p * r + 1.0 / 40320.0; p = p * r + 1.0 / 5040.0;
;     p = p * r + 1.0 / 720.0; p = p * r + 1.0 / 120.0; p = p * r + 1.0 / 24.0; p = p * r + 1.0 / 6.0; p = p * r + 0.5; p = p * r + 1.0; p = p * r + 1.0;
;     const long long bits = ((long long)((int)k + 1023)) << 52;
;     return p * __builtin_bit_cast(double, bits);
; }
; __device__ __forceinline__ void p0_prologue(const Args& args, LAS unsigned char* lds, int tid, int lane, int wave, int bx, int G) {
;     ...
;     if (gt < DEPTH * NG * NP) {
;         const int L = gt >> 11, gp = gt & 2047, g = gp >> 6;
;         float* tb = (float*)(ws + WS_TB) + (size_t)L * TB_LAYER;
;         double lr = (double)GIN(I_LRE)[L * 2048 + gp]; lr = lr < -1e-4 ? lr : -1e-4;
;         const double li = (double)GIN(I_LIM)[L * 2048 + gp];
;         const double dt = dexp((double)GIN(I_LDT)[L * NG + g]);
;         const double mag = dexp(lr * dt); double sn, cs; dsincos(li * dt, sn, cs);
.LBB0_83:
	v_readlane_b32 s2, v252, 0
	s_load_dword s3, s[0:1], 0x120
	s_waitcnt lgkmcnt(0)
	s_cmpk_lg_i32 s3, 0x100
	s_cbranch_scc1 .Lp0t_keep
	s_addk_i32 s2, 0xff80
	s_cmp_lt_i32 s2, 0
	s_cselect_b32 s2, 0x4000, s2
.Lp0t_keep:
	v_lshl_or_b32 v2, s2, 9, v0
	s_movk_i32 s2, 0x1000
	v_cmp_gt_i32_e32 vcc, s2, v2
	v_ashrrev_i32_e32 v3, 31, v2
	s_and_saveexec_b64 s[4:5], vcc
	s_cbranch_execz .LBB0_91
	s_load_dwordx16 s[16:31], s[0:1], 0x40
	v_lshlrev_b64 v[4:5], 2, v[2:3]
	s_mov_b32 s14, 0xfee00000
	s_mov_b32 s15, 0xbfe62e42
	s_mov_b32 s6, 0x35793c76
	s_waitcnt lgkmcnt(0)
	s_mov_b64 s[2:3], s[16:17]
	s_mov_b32 s16, 0x652b82fe
	v_lshl_add_u64 v[6:7], s[2:3], 0, v[4:5]
	s_mov_b64 s[2:3], s[18:19]
	global_load_dword v29, v[6:7], off
	v_ashrrev_i32_e32 v6, 11, v2
	v_lshl_add_u64 v[4:5], s[2:3], 0, v[4:5]
	global_load_dword v4, v[4:5], off
	v_bfe_u32 v5, v2, 6, 5
	v_lshl_or_b32 v8, v6, 5, v5
	s_mov_b64 s[2:3], s[20:21]
	v_ashrrev_i32_e32 v9, 31, v8
	s_mov_b32 s17, 0x3ff71547
	v_lshl_add_u64 v[8:9], v[8:9], 2, s[2:3]
	global_load_dword v7, v[8:9], off
	s_mov_b32 s22, 0xeff8d898
	s_mov_b32 s7, 0xbdea39ef
	s_mov_b32 s23, 0x3e21eed8
	s_mov_b32 s2, 0x13a86d09
	s_mov_b32 s3, 0x3de61246
	v_mov_b64_e32 v[36:37], s[22:23]
	v_mov_b32_e32 v12, 0x67f544e4
	v_mov_b32_e32 v13, 0x3e5ae645
	v_mov_b32_e32 v10, 0xb7789f5c
	v_mov_b32_e32 v11, 0x3e927e4f
	s_mov_b32 s18, 0xa556c734
	s_mov_b32 s19, 0x3ec71de3
	s_mov_b32 s20, 0x1a01a01a
	s_mov_b32 s21, 0x3efa01a0
	v_mov_b32_e32 v16, 0x1a01a01a
	v_mov_b32_e32 v17, 0x3f2a01a0
	v_mov_b32_e32 v14, 0x16c16c17
	v_mov_b32_e32 v15, 0x3f56c16c
	s_mov_b32 s24, 0x11111111
	s_mov_b32 s25, 0x3f811111
	s_mov_b32 s26, 0x55555555
	s_mov_b32 s27, 0x3fa55555
	v_mov_b32_e32 v18, 0x55555555
	v_mov_b32_e32 v19, 0x3fc55555
	v_mov_b32_e32 v30, 0x3ff00000
	v_mov_b32_e32 v8, 0
	s_mov_b32 s34, 0x6dc9c883
	s_mov_b32 s35, 0x3fe45f30
	s_mov_b32 s36, 0x54442d18
	s_mov_b32 s37, 0xbff921fb
	s_mov_b32 s30, 0x33145c07
	s_mov_b32 s31, 0xbc91a626
	s_mov_b32 s28, 0xe733b81f
	s_mov_b32 s29, 0xbd6ae7f3
	s_mov_b32 s38, 0xa8c07c9d
	v_mov_b64_e32 v[38:39], s[2:3]
	v_mov_b32_e32 v21, 0xbe5ae645
	s_mov_b32 s39, 0xbda93974
	v_mov_b32_e32 v20, v12
	v_mov_b32_e32 v33, 0xbe927e4f
	v_mov_b32_e32 v32, v10
	v_mov_b32_e32 v23, 0xbf2a01a0
	v_mov_b32_e32 v22, v16
	v_mov_b32_e32 v35, 0xbf56c16c
	v_mov_b32_e32 v34, v14
	v_mov_b32_e32 v27, 0xbfc55555
	v_mov_b32_e32 v26, v18
	v_and_b32_e32 v28, 0x7ff, v2
	s_waitcnt vmcnt(1)
	v_cvt_f64_f32_e32 v[4:5], v4
	s_waitcnt vmcnt(0)
	v_cvt_f64_f32_e32 v[24:25], v7
	v_mul_f64 v[40:41], v[24:25], s[16:17]
	v_rndne_f64_e32 v[40:41], v[40:41]
	v_fmac_f64_e32 v[24:25], s[14:15], v[40:41]
	v_fmac_f64_e32 v[24:25], s[6:7], v[40:41]
	v_cvt_i32_f64_e32 v7, v[40:41]
	v_fma_f64 v[40:41], s[2:3], v[24:25], v[36:37]
	v_fma_f64 v[40:41], v[24:25], v[40:41], v[12:13]
	v_fma_f64 v[40:41], v[24:25], v[40:41], v[10:11]
	v_fma_f64 v[40:41], v[24:25], v[40:41], s[18:19]
	v_fma_f64 v[40:41], v[24:25], v[40:41], s[20:21]
	v_fma_f64 v[40:41], v[24:25], v[40:41], v[16:17]
	v_fma_f64 v[40:41], v[24:25], v[40:41], v[14:15]
	v_fma_f64 v[40:41], v[24:25], v[40:41], s[24:25]
	v_fma_f64 v[40:41], v[24:25], v[40:41], s[26:27]
	v_fma_f64 v[40:41], v[24:25], v[40:41], v[18:19]
	v_fma_f64 v[40:41], v[24:25], v[40:41], 0.5
	v_fma_f64 v[40:41], v[24:25], v[40:41], 1.0
	v_lshl_add_u32 v9, v7, 20, v30
	v_fma_f64 v[24:25], v[24:25], v[40:41], 1.0
	v_mul_f64 v[24:25], v[24:25], v[8:9]
	v_mul_f64 v[40:41], v[24:25], v[4:5]
	v_mul_f64 v[42:43], v[40:41], s[34:35]
	v_rndne_f64_e32 v[42:43], v[42:43]
	v_fmac_f64_e32 v[40:41], s[36:37], v[42:43]
	v_fmac_f64_e32 v[40:41], s[30:31], v[42:43]
	v_cvt_i32_f64_e32 v7, v[42:43]
	v_mul_f64 v[42:43], v[40:41], v[40:41]
	v_fma_f64 v[38:39], s[28:29], v[42:43], v[38:39]
	v_fmac_f64_e32 v[36:37], s[38:39], v[42:43]
	v_fmac_f64_e32 v[20:21], v[42:43], v[38:39]
	v_fmac_f64_e32 v[32:33], v[42:43], v[36:37]
	v_fma_f64 v[20:21], v[42:43], v[20:21], s[18:19]
	v_fma_f64 v[32:33], v[42:43], v[32:33], s[20:21]
	v_fmac_f64_e32 v[22:23], v[42:43], v[20:21]
	v_fmac_f64_e32 v[34:35], v[42:43], v[32:33]
	v_fma_f64 v[20:21], v[42:43], v[22:23], s[24:25]
	v_fma_f64 v[22:23], v[42:43], v[34:35], s[26:27]
	v_fmac_f64_e32 v[26:27], v[42:43], v[20:21]
	v_and_b32_e32 v7, 3, v7
	v_fma_f64 v[20:21], v[42:43], v[22:23], -0.5
	v_fma_f64 v[22:23], v[42:43], v[26:27], 1.0
	v_fma_f64 v[20:21], v[42:43], v[20:21], 1.0
	v_mul_f64 v[22:23], v[40:41], v[22:23]
	v_cmp_lt_i32_e32 vcc, 0, v7
	s_and_saveexec_b64 s[18:19], vcc
	s_cbranch_execz .LBB0_90
	v_cmp_ne_u32_e32 vcc, 1, v7
	v_xor_b32_e32 v27, 0x80000000, v23
	v_mov_b32_e32 v26, v22
	s_and_saveexec_b64 s[20:21], vcc
	s_xor_b64 s[20:21], exec, s[20:21]
	v_cmp_eq_u32_e32 vcc, 2, v7
	v_xor_b32_e32 v7, 0x80000000, v21
	s_nop 0
	v_cndmask_b32_e32 v32, v20, v22, vcc
	v_cndmask_b32_e64 v33, -v21, -v23, vcc
	v_cndmask_b32_e32 v27, v23, v7, vcc
	v_cndmask_b32_e32 v26, v22, v20, vcc
	v_mov_b64_e32 v[22:23], v[32:33]
	s_andn2_saveexec_b64 s[20:21], s[20:21]
	v_mov_b64_e32 v[22:23], v[20:21]
	s_or_b64 exec, exec, s[20:21]
	v_mov_b64_e32 v[20:21], v[26:27]

; #define GIN(i) GPTR(const float, args.in[i])
; __device__ __forceinline__ void p0_prologue(const Args& args, LAS unsigned char* lds, int tid, int lane, int wave, int bx, int G) {
;     ...
;     for (int e = gt; e < DEPTH * NG * NP * (S5T + 1); e += NGT) {
;         const int d = e % (S5T + 1), lgp = e / (S5T + 1), p = lgp & 63, lg = lgp >> 6;
;         double lr = (double)GIN(I_LRE)[lgp]; lr = lr < -1e-4 ? lr : -1e-4; const double li = (double)GIN(I_LIM)[lgp];
;         const double dt = dexp((double)GIN(I_LDT)[lg]);
;         const double md = dexp(lr * dt * (double)d); double sd, cd; dsincos(li * dt * (double)d, sd, cd);
;         float* lp = (float*)(ws + WS_LPOW) + (((size_t)lg * (S5T + 1) + d) * NP + p) * 2; lp[0] = (float)(md * cd); lp[1] = (float)(md * sd);
;     }
.LBB0_91:
	s_or_b64 exec, exec, s[4:5]
	v_readlane_b32 s2, v252, 0
	s_nop 1
	v_lshl_or_b32 v2, s2, 9, v0
	v_ashrrev_i32_e32 v3, 31, v2
	s_load_dword s2, s[0:1], 0x120
	s_mov_b32 s3, 0x21000
	v_cmp_gt_i32_e32 vcc, s3, v2
	s_waitcnt lgkmcnt(0)
	s_lshl_b32 s2, s2, 9
	s_and_saveexec_b64 s[4:5], vcc
	s_cbranch_execz .LBB0_100
	s_mov_b32 s24, 0xeff8d898
	s_mov_b32 s25, 0x3e21eed8
	s_mov_b32 s22, 0x13a86d09
	s_add_u32 s6, s12, 0x7780000
	s_mov_b32 s16, 0x652b82fe
	s_mov_b32 s18, 0xfee00000
	s_mov_b32 s20, 0x35793c76
	s_mov_b32 s23, 0x3de61246
	v_mov_b64_e32 v[4:5], s[24:25]
	v_mov_b32_e32 v6, 0x67f544e4
	v_mov_b32_e32 v8, 0xb7789f5c
	s_mov_b32 s24, 0xa556c734
	s_mov_b32 s26, 0x1a01a01a
	v_mov_b32_e32 v13, 0x3f2a01a0
	v_mov_b32_e32 v16, 0x16c16c17
	s_mov_b32 s28, 0x11111111
	s_mov_b32 s30, 0x55555555
	v_mov_b32_e32 v21, 0x3fc55555
	s_mov_b32 s34, 0x6dc9c883
	s_mov_b32 s36, 0x54442d18
	s_mov_b32 s38, 0x33145c07
	s_mov_b32 s40, 0xe733b81f
	s_mov_b32 s42, 0xa8c07c9d
	s_mov_b32 s44, 0xeb1c432d
	s_addc_u32 s7, s13, 0
	s_mov_b64 s[14:15], 0
	s_mov_b32 s17, 0x3ff71547
	s_mov_b32 s19, 0xbfe62e42
	s_mov_b32 s21, 0xbdea39ef
	v_mov_b32_e32 v7, 0x3e5ae645
	v_mov_b32_e32 v9, 0x3e927e4f
	s_mov_b32 s25, 0x3ec71de3
	s_mov_b32 s27, 0x3efa01a0
	v_mov_b32_e32 v10, 0x1a01a01a
	v_mov_b32_e32 v14, 0x1a01a01a
	v_mov_b32_e32 v15, v13
	v_mov_b32_e32 v17, 0x3f56c16c
	s_mov_b32 s29, 0x3f811111
	s_mov_b32 s31, 0x3fa55555
	v_mov_b32_e32 v18, 0x55555555
	v_mov_b32_e32 v22, 0x55555555
	v_mov_b32_e32 v23, v21
	v_mov_b32_e32 v45, 0x3ff00000
	v_mov_b32_e32 v24, 0
	s_mov_b32 s35, 0x3fe45f30
	s_mov_b32 s37, 0xbff921fb
	s_mov_b32 s39, 0xbc91a626
	s_mov_b32 s41, 0xbd6ae7f3
	v_mov_b64_e32 v[26:27], s[22:23]
	v_mov_b32_e32 v29, 0xbe5ae645
	v_mov_b32_e32 v28, v6
	v_mov_b32_e32 v31, 0xbf2a01a0
	v_mov_b32_e32 v30, 0x1a01a01a
	v_mov_b32_e32 v33, 0xbfc55555
	v_mov_b32_e32 v32, 0x55555555
	s_mov_b32 s43, 0xbda93974
	v_mov_b32_e32 v35, 0xbe927e4f
	v_mov_b32_e32 v34, v8
	v_mov_b32_e32 v37, 0xbf56c16c
	v_mov_b32_e32 v36, v16
	s_mov_b32 s45, 0xbf1a36e2
	v_mov_b32_e32 v38, 0xeff8d898
	v_mov_b32_e32 v39, 0x3e21eed8
	v_mov_b32_e32 v40, 0xa556c734
	v_mov_b32_e32 v41, 0x3ec71de3
	v_mov_b32_e32 v11, 0x3efa01a0
	v_mov_b32_e32 v42, 0x11111111
	v_mov_b32_e32 v43, 0x3f811111
	v_mov_b32_e32 v19, 0x3fa55555
	v_mov_b32_e32 v44, v2
	s_cmp_lg_u32 s2, 0x20000
	s_cbranch_scc1 .Lp0l_keep
	v_add_u32_e32 v44, 0xfffef000, v2
	v_and_b32_e32 v44, 0x1ffff, v44
.Lp0l_keep:
	s_branch .LBB0_95
.LBB0_93:
	s_or_b64 exec, exec, s[48:49]
	v_mov_b64_e32 v[56:57], v[62:63]
